# GEMM1 SwiGLU epilogue: 1/sqrt via v_rsq_f32 instead of expanded sqrt+div chain; epilogue-start vmcnt(0) relaxed to vmcnt(8)
# speedup vs baseline: 1.0088x; 1.0078x over previous
.LBB0_384:
	s_waitcnt vmcnt(8)
	v_fmamk_f32 v145, v163, 0x3a800000, v154
	v_rsq_f32_e32 v145, v145
	s_nop 1
	s_nop 0
	s_nop 1
	s_nop 1
	v_lshl_or_b32 v148, s60, 7, v152
	v_ashrrev_i32_e32 v149, 31, v148
	v_lshlrev_b64 v[148:149], 1, v[148:149]
	v_mov_b32_e32 v164, v145
	v_pk_mul_f32 v[124:125], v[124:125], v[164:165] op_sel_hi:[1,0]
	v_pk_mul_f32 v[126:127], v[126:127], v[164:165] op_sel_hi:[1,0]
	v_pk_mul_f32 v[122:123], v[122:123], v[164:165] op_sel_hi:[1,0]
	v_pk_mul_f32 v[120:121], v[120:121], v[164:165] op_sel_hi:[1,0]
	v_pk_mul_f32 v[118:119], v[118:119], v[164:165] op_sel_hi:[1,0]
	v_pk_mul_f32 v[116:117], v[116:117], v[164:165] op_sel_hi:[1,0]
	v_mul_f32_e32 v145, 0xbfb8aa3b, v124
	v_mul_f32_e32 v165, 0xbfb8aa3b, v125
	v_exp_f32_e32 v145, v145
	v_exp_f32_e32 v165, v165
	v_mov_b64_e32 v[146:147], s[12:13]
	v_mad_i64_i32 v[166:167], s[8:9], v144, s59, v[146:147]
	v_pk_mul_f32 v[168:169], v[114:115], v[164:165] op_sel_hi:[1,0]
	v_add_f32_e32 v114, 1.0, v145
	v_rcp_f32_e32 v145, v114
	v_add_f32_e32 v114, 1.0, v165
	v_rcp_f32_e32 v165, v114
	v_lshl_add_u64 v[166:167], v[166:167], 0, v[148:149]
	v_pk_mul_f32 v[114:115], v[112:113], v[164:165] op_sel_hi:[1,0]
	v_mul_f32_e32 v112, v124, v145
	v_mul_f32_e32 v112, v116, v112
	v_mul_f32_e32 v116, 0xbfb8aa3b, v126
	v_mul_f32_e32 v124, 0xbfb8aa3b, v127
	v_exp_f32_e32 v116, v116
	v_exp_f32_e32 v124, v124
	v_mul_f32_e32 v113, v125, v165
	v_mul_f32_e32 v113, v117, v113
	v_add_f32_e32 v116, 1.0, v116
	v_add_f32_e32 v117, 1.0, v124
	v_rcp_f32_e32 v116, v116
	v_rcp_f32_e32 v117, v117
	v_cvt_pk_bf16_f32 v112, v112, v113
	v_mul_f32_e32 v113, v126, v116
	v_mul_f32_e32 v116, v127, v117
	v_mul_f32_e32 v117, 0xbfb8aa3b, v120
	v_mul_f32_e32 v113, v118, v113
	v_exp_f32_e32 v117, v117
	v_mul_f32_e32 v118, 0xbfb8aa3b, v121
	v_exp_f32_e32 v118, v118
	v_mul_f32_e32 v116, v119, v116
	v_cvt_pk_bf16_f32 v113, v113, v116
	v_add_f32_e32 v116, 1.0, v117
	v_rcp_f32_e32 v116, v116
	v_add_f32_e32 v117, 1.0, v118
	v_mul_f32_e32 v118, 0xbfb8aa3b, v122
	v_rcp_f32_e32 v117, v117
	v_exp_f32_e32 v118, v118
	v_mul_f32_e32 v116, v120, v116
	v_mul_f32_e32 v114, v114, v116
	v_mul_f32_e32 v116, v121, v117
	v_add_f32_e32 v117, 1.0, v118
	v_rcp_f32_e32 v117, v117
	v_mul_f32_e32 v118, 0xbfb8aa3b, v123
	v_exp_f32_e32 v118, v118
	v_mul_f32_e32 v115, v115, v116
	v_cvt_pk_bf16_f32 v114, v114, v115
	v_mul_f32_e32 v115, v122, v117
	v_fmamk_f32 v117, v162, 0x3a800000, v154
	v_rsq_f32_e32 v117, v117
	v_add_f32_e32 v116, 1.0, v118
	v_rcp_f32_e32 v116, v116
	v_mul_f32_e32 v115, v168, v115
	v_mul_f32_e32 v116, v123, v116
	v_mul_f32_e32 v116, v169, v116
	v_cvt_pk_bf16_f32 v115, v115, v116
	flat_store_dwordx4 v[166:167], v[112:115]
	s_nop 1
	v_or_b32_e32 v113, 16, v144
	s_nop 0
	s_nop 1
	s_nop 0
	v_mov_b32_e32 v112, v117
	v_pk_mul_f32 v[108:109], v[112:113], v[108:109] op_sel_hi:[0,1]
	v_mad_i64_i32 v[114:115], s[8:9], v113, s59, v[146:147]
	v_pk_mul_f32 v[110:111], v[112:113], v[110:111] op_sel_hi:[0,1]
	v_pk_mul_f32 v[106:107], v[112:113], v[106:107] op_sel_hi:[0,1]
	v_pk_mul_f32 v[104:105], v[112:113], v[104:105] op_sel_hi:[0,1]
	v_pk_mul_f32 v[102:103], v[112:113], v[102:103] op_sel_hi:[0,1]
	v_pk_mul_f32 v[100:101], v[112:113], v[100:101] op_sel_hi:[0,1]
	v_mul_f32_e32 v113, 0xbfb8aa3b, v108
	v_exp_f32_e32 v113, v113
	v_mul_f32_e32 v116, 0xbfb8aa3b, v109
	v_exp_f32_e32 v118, v116
	v_lshl_add_u64 v[114:115], v[114:115], 0, v[148:149]
	v_pk_mul_f32 v[116:117], v[112:113], v[98:99] op_sel_hi:[0,1]
	v_add_f32_e32 v98, 1.0, v113
	v_rcp_f32_e32 v113, v98
	v_add_f32_e32 v98, 1.0, v118
	v_rcp_f32_e32 v118, v98
	v_pk_mul_f32 v[98:99], v[112:113], v[96:97] op_sel_hi:[0,1]
	v_mul_f32_e32 v96, v108, v113
	v_mul_f32_e32 v96, v100, v96
	v_mul_f32_e32 v100, 0xbfb8aa3b, v110
	v_mul_f32_e32 v108, 0xbfb8aa3b, v111
	v_exp_f32_e32 v100, v100
	v_exp_f32_e32 v108, v108
	v_mul_f32_e32 v97, v109, v118
	v_mul_f32_e32 v97, v101, v97
	v_add_f32_e32 v100, 1.0, v100
	v_add_f32_e32 v101, 1.0, v108
	v_rcp_f32_e32 v100, v100
	v_rcp_f32_e32 v101, v101
	v_cvt_pk_bf16_f32 v96, v96, v97
	v_mul_f32_e32 v97, v110, v100
	v_mul_f32_e32 v100, v111, v101
	v_mul_f32_e32 v101, 0xbfb8aa3b, v104
	v_mul_f32_e32 v97, v102, v97
	v_exp_f32_e32 v101, v101
	v_mul_f32_e32 v102, 0xbfb8aa3b, v105
	v_exp_f32_e32 v102, v102
	v_mul_f32_e32 v100, v103, v100
	v_cvt_pk_bf16_f32 v97, v97, v100
	v_add_f32_e32 v100, 1.0, v101
	v_rcp_f32_e32 v100, v100
	v_add_f32_e32 v101, 1.0, v102
	v_mul_f32_e32 v102, 0xbfb8aa3b, v106
	v_rcp_f32_e32 v101, v101
	v_exp_f32_e32 v102, v102
	v_mul_f32_e32 v100, v104, v100
	v_mul_f32_e32 v98, v98, v100
	v_mul_f32_e32 v100, v105, v101
	v_add_f32_e32 v101, 1.0, v102
	v_rcp_f32_e32 v101, v101
	v_mul_f32_e32 v102, 0xbfb8aa3b, v107
	v_exp_f32_e32 v102, v102
	v_mul_f32_e32 v99, v99, v100
	v_cvt_pk_bf16_f32 v98, v98, v99
	v_mul_f32_e32 v99, v106, v101
	v_fmamk_f32 v101, v161, 0x3a800000, v154
	v_rsq_f32_e32 v101, v101
	v_add_f32_e32 v100, 1.0, v102
	v_rcp_f32_e32 v100, v100
	v_mul_f32_e32 v99, v116, v99
	v_mul_f32_e32 v100, v107, v100
	v_mul_f32_e32 v100, v117, v100
	v_cvt_pk_bf16_f32 v99, v99, v100
	flat_store_dwordx4 v[114:115], v[96:99]
	s_nop 1
	v_or_b32_e32 v97, 32, v144
	s_nop 0
	s_nop 1
	s_nop 0
	v_mov_b32_e32 v96, v101
	v_pk_mul_f32 v[92:93], v[96:97], v[92:93] op_sel_hi:[0,1]
	v_mad_i64_i32 v[98:99], s[8:9], v97, s59, v[146:147]
	v_pk_mul_f32 v[94:95], v[96:97], v[94:95] op_sel_hi:[0,1]
	v_pk_mul_f32 v[90:91], v[96:97], v[90:91] op_sel_hi:[0,1]
	v_pk_mul_f32 v[88:89], v[96:97], v[88:89] op_sel_hi:[0,1]
	v_pk_mul_f32 v[86:87], v[96:97], v[86:87] op_sel_hi:[0,1]
	v_pk_mul_f32 v[84:85], v[96:97], v[84:85] op_sel_hi:[0,1]
	v_mul_f32_e32 v97, 0xbfb8aa3b, v92
	v_exp_f32_e32 v97, v97
	v_mul_f32_e32 v100, 0xbfb8aa3b, v93
	v_exp_f32_e32 v102, v100
	v_lshl_add_u64 v[98:99], v[98:99], 0, v[148:149]
	v_pk_mul_f32 v[100:101], v[96:97], v[82:83] op_sel_hi:[0,1]
	v_add_f32_e32 v82, 1.0, v97
	v_rcp_f32_e32 v97, v82
	v_add_f32_e32 v82, 1.0, v102
	v_rcp_f32_e32 v102, v82
	v_pk_mul_f32 v[82:83], v[96:97], v[80:81] op_sel_hi:[0,1]
	v_mul_f32_e32 v80, v92, v97
	v_mul_f32_e32 v80, v84, v80
	v_mul_f32_e32 v84, 0xbfb8aa3b, v94
	v_mul_f32_e32 v92, 0xbfb8aa3b, v95
	v_exp_f32_e32 v84, v84
	v_exp_f32_e32 v92, v92
	v_mul_f32_e32 v81, v93, v102
	v_mul_f32_e32 v81, v85, v81
	v_add_f32_e32 v84, 1.0, v84
	v_add_f32_e32 v85, 1.0, v92
	v_rcp_f32_e32 v84, v84
	v_rcp_f32_e32 v85, v85
	v_cvt_pk_bf16_f32 v80, v80, v81
	v_mul_f32_e32 v81, v94, v84
	v_mul_f32_e32 v84, v95, v85
	v_mul_f32_e32 v85, 0xbfb8aa3b, v88
	v_mul_f32_e32 v81, v86, v81
	v_exp_f32_e32 v85, v85
	v_mul_f32_e32 v86, 0xbfb8aa3b, v89
	v_exp_f32_e32 v86, v86
	v_mul_f32_e32 v84, v87, v84
	v_cvt_pk_bf16_f32 v81, v81, v84
	v_add_f32_e32 v84, 1.0, v85
	v_rcp_f32_e32 v84, v84
	v_add_f32_e32 v85, 1.0, v86
	v_mul_f32_e32 v86, 0xbfb8aa3b, v90
	v_rcp_f32_e32 v85, v85
	v_exp_f32_e32 v86, v86
	v_mul_f32_e32 v84, v88, v84
	v_mul_f32_e32 v82, v82, v84
	v_mul_f32_e32 v84, v89, v85
	v_add_f32_e32 v85, 1.0, v86
	v_rcp_f32_e32 v85, v85
	v_mul_f32_e32 v86, 0xbfb8aa3b, v91
	v_exp_f32_e32 v86, v86
	v_mul_f32_e32 v83, v83, v84
	v_cvt_pk_bf16_f32 v82, v82, v83
	v_mul_f32_e32 v83, v90, v85
	v_fmamk_f32 v85, v160, 0x3a800000, v154
	v_rsq_f32_e32 v85, v85
	v_add_f32_e32 v84, 1.0, v86
	v_rcp_f32_e32 v84, v84
	v_mul_f32_e32 v83, v100, v83
	v_mul_f32_e32 v84, v91, v84
	v_mul_f32_e32 v84, v101, v84
	v_cvt_pk_bf16_f32 v83, v83, v84
	flat_store_dwordx4 v[98:99], v[80:83]
	s_nop 1
	v_or_b32_e32 v81, 48, v144
	s_nop 0
	s_nop 1
	s_nop 0
	v_mov_b32_e32 v80, v85
	v_pk_mul_f32 v[76:77], v[80:81], v[76:77] op_sel_hi:[0,1]
	v_mad_i64_i32 v[82:83], s[8:9], v81, s59, v[146:147]
	v_pk_mul_f32 v[78:79], v[80:81], v[78:79] op_sel_hi:[0,1]
	v_pk_mul_f32 v[74:75], v[80:81], v[74:75] op_sel_hi:[0,1]
	v_pk_mul_f32 v[72:73], v[80:81], v[72:73] op_sel_hi:[0,1]
	v_pk_mul_f32 v[70:71], v[80:81], v[70:71] op_sel_hi:[0,1]
	v_pk_mul_f32 v[68:69], v[80:81], v[68:69] op_sel_hi:[0,1]
	v_mul_f32_e32 v81, 0xbfb8aa3b, v76
	v_exp_f32_e32 v81, v81
	v_mul_f32_e32 v84, 0xbfb8aa3b, v77
	v_exp_f32_e32 v86, v84
	v_lshl_add_u64 v[82:83], v[82:83], 0, v[148:149]
	v_pk_mul_f32 v[84:85], v[80:81], v[66:67] op_sel_hi:[0,1]
	v_add_f32_e32 v66, 1.0, v81
	v_rcp_f32_e32 v81, v66
	v_add_f32_e32 v66, 1.0, v86
	v_rcp_f32_e32 v86, v66
	v_pk_mul_f32 v[66:67], v[80:81], v[64:65] op_sel_hi:[0,1]
	v_mul_f32_e32 v64, v76, v81
	v_mul_f32_e32 v64, v68, v64
	v_mul_f32_e32 v68, 0xbfb8aa3b, v78
	v_mul_f32_e32 v76, 0xbfb8aa3b, v79
	v_exp_f32_e32 v68, v68
	v_exp_f32_e32 v76, v76
	v_mul_f32_e32 v65, v77, v86
	v_mul_f32_e32 v65, v69, v65
	v_add_f32_e32 v68, 1.0, v68
	v_add_f32_e32 v69, 1.0, v76
	v_rcp_f32_e32 v68, v68
	v_rcp_f32_e32 v69, v69
	v_cvt_pk_bf16_f32 v64, v64, v65
	v_mul_f32_e32 v65, v78, v68
	v_mul_f32_e32 v68, v79, v69
	v_mul_f32_e32 v69, 0xbfb8aa3b, v72
	v_mul_f32_e32 v65, v70, v65
	v_exp_f32_e32 v69, v69
	v_mul_f32_e32 v70, 0xbfb8aa3b, v73
	v_exp_f32_e32 v70, v70
	v_mul_f32_e32 v68, v71, v68
	v_cvt_pk_bf16_f32 v65, v65, v68
	v_add_f32_e32 v68, 1.0, v69
	v_rcp_f32_e32 v68, v68
	v_add_f32_e32 v69, 1.0, v70
	v_mul_f32_e32 v70, 0xbfb8aa3b, v74
	v_rcp_f32_e32 v69, v69
	v_exp_f32_e32 v70, v70
	v_mul_f32_e32 v68, v72, v68
	v_mul_f32_e32 v66, v66, v68
	v_mul_f32_e32 v68, v73, v69
	v_add_f32_e32 v69, 1.0, v70
	v_rcp_f32_e32 v69, v69
	v_mul_f32_e32 v70, 0xbfb8aa3b, v75
	v_exp_f32_e32 v70, v70
	v_mul_f32_e32 v67, v67, v68
	v_cvt_pk_bf16_f32 v66, v66, v67
	v_mul_f32_e32 v67, v74, v69
	v_fmamk_f32 v69, v159, 0x3a800000, v154
	v_rsq_f32_e32 v69, v69
	v_add_f32_e32 v68, 1.0, v70
	v_rcp_f32_e32 v68, v68
	v_mul_f32_e32 v67, v84, v67
	v_mul_f32_e32 v68, v75, v68
	v_mul_f32_e32 v68, v85, v68
	v_cvt_pk_bf16_f32 v67, v67, v68
	flat_store_dwordx4 v[82:83], v[64:67]
	s_nop 1
	v_add_u32_e32 v65, 0x80, v144
	s_nop 0
	s_nop 1
	s_nop 0
	v_mov_b32_e32 v64, v69
	v_pk_mul_f32 v[60:61], v[64:65], v[60:61] op_sel_hi:[0,1]
	v_mad_i64_i32 v[66:67], s[8:9], v65, s59, v[146:147]
	v_pk_mul_f32 v[62:63], v[64:65], v[62:63] op_sel_hi:[0,1]
	v_pk_mul_f32 v[58:59], v[64:65], v[58:59] op_sel_hi:[0,1]
	v_pk_mul_f32 v[56:57], v[64:65], v[56:57] op_sel_hi:[0,1]
	v_pk_mul_f32 v[54:55], v[64:65], v[54:55] op_sel_hi:[0,1]
	v_pk_mul_f32 v[52:53], v[64:65], v[52:53] op_sel_hi:[0,1]
	v_mul_f32_e32 v65, 0xbfb8aa3b, v60
	v_exp_f32_e32 v65, v65
	v_mul_f32_e32 v68, 0xbfb8aa3b, v61
	v_exp_f32_e32 v70, v68
	v_lshl_add_u64 v[66:67], v[66:67], 0, v[148:149]
	v_pk_mul_f32 v[68:69], v[64:65], v[50:51] op_sel_hi:[0,1]
	v_add_f32_e32 v50, 1.0, v65
	v_rcp_f32_e32 v65, v50
	v_add_f32_e32 v50, 1.0, v70
	v_rcp_f32_e32 v70, v50
	v_pk_mul_f32 v[50:51], v[64:65], v[48:49] op_sel_hi:[0,1]
	v_mul_f32_e32 v48, v60, v65
	v_mul_f32_e32 v48, v52, v48
	v_mul_f32_e32 v52, 0xbfb8aa3b, v62
	v_mul_f32_e32 v60, 0xbfb8aa3b, v63
	v_exp_f32_e32 v52, v52
	v_exp_f32_e32 v60, v60
	v_mul_f32_e32 v49, v61, v70
	v_mul_f32_e32 v49, v53, v49
	v_add_f32_e32 v52, 1.0, v52
	v_add_f32_e32 v53, 1.0, v60
	v_rcp_f32_e32 v52, v52
	v_rcp_f32_e32 v53, v53
	v_cvt_pk_bf16_f32 v48, v48, v49
	v_mul_f32_e32 v49, v62, v52
	v_mul_f32_e32 v52, v63, v53
	v_mul_f32_e32 v53, 0xbfb8aa3b, v56
	v_mul_f32_e32 v49, v54, v49
	v_exp_f32_e32 v53, v53
	v_mul_f32_e32 v54, 0xbfb8aa3b, v57
	v_exp_f32_e32 v54, v54
	v_mul_f32_e32 v52, v55, v52
	v_cvt_pk_bf16_f32 v49, v49, v52
	v_add_f32_e32 v52, 1.0, v53
	v_rcp_f32_e32 v52, v52
	v_add_f32_e32 v53, 1.0, v54
	v_mul_f32_e32 v54, 0xbfb8aa3b, v58
	v_rcp_f32_e32 v53, v53
	v_exp_f32_e32 v54, v54
	v_mul_f32_e32 v52, v56, v52
	v_mul_f32_e32 v50, v50, v52
	v_mul_f32_e32 v52, v57, v53
	v_add_f32_e32 v53, 1.0, v54
	v_rcp_f32_e32 v53, v53
	v_mul_f32_e32 v54, 0xbfb8aa3b, v59
	v_exp_f32_e32 v54, v54
	v_mul_f32_e32 v51, v51, v52
	v_cvt_pk_bf16_f32 v50, v50, v51
	v_mul_f32_e32 v51, v58, v53
	v_fmamk_f32 v53, v158, 0x3a800000, v154
	v_rsq_f32_e32 v53, v53
	v_add_f32_e32 v52, 1.0, v54
	v_rcp_f32_e32 v52, v52
	v_mul_f32_e32 v51, v68, v51
	v_mul_f32_e32 v52, v59, v52
	v_mul_f32_e32 v52, v69, v52
	v_cvt_pk_bf16_f32 v51, v51, v52
	flat_store_dwordx4 v[66:67], v[48:51]
	s_nop 1
	v_add_u32_e32 v49, 0x90, v144
	s_nop 0
	s_nop 1
	s_nop 0
	v_mov_b32_e32 v48, v53
	v_pk_mul_f32 v[44:45], v[48:49], v[44:45] op_sel_hi:[0,1]
	v_mad_i64_i32 v[50:51], s[8:9], v49, s59, v[146:147]
	v_pk_mul_f32 v[46:47], v[48:49], v[46:47] op_sel_hi:[0,1]
	v_pk_mul_f32 v[42:43], v[48:49], v[42:43] op_sel_hi:[0,1]
	v_pk_mul_f32 v[40:41], v[48:49], v[40:41] op_sel_hi:[0,1]
	v_pk_mul_f32 v[38:39], v[48:49], v[38:39] op_sel_hi:[0,1]
	v_pk_mul_f32 v[36:37], v[48:49], v[36:37] op_sel_hi:[0,1]
	v_mul_f32_e32 v49, 0xbfb8aa3b, v44
	v_exp_f32_e32 v49, v49
	v_mul_f32_e32 v52, 0xbfb8aa3b, v45
	v_exp_f32_e32 v54, v52
	v_lshl_add_u64 v[50:51], v[50:51], 0, v[148:149]
	v_pk_mul_f32 v[52:53], v[48:49], v[34:35] op_sel_hi:[0,1]
	v_add_f32_e32 v34, 1.0, v49
	v_rcp_f32_e32 v49, v34
	v_add_f32_e32 v34, 1.0, v54
	v_rcp_f32_e32 v54, v34
	v_pk_mul_f32 v[34:35], v[48:49], v[32:33] op_sel_hi:[0,1]
	v_mul_f32_e32 v32, v44, v49
	v_mul_f32_e32 v32, v36, v32
	v_mul_f32_e32 v36, 0xbfb8aa3b, v46
	v_mul_f32_e32 v44, 0xbfb8aa3b, v47
	v_exp_f32_e32 v36, v36
	v_exp_f32_e32 v44, v44
	v_mul_f32_e32 v33, v45, v54
	v_mul_f32_e32 v33, v37, v33
	v_add_f32_e32 v36, 1.0, v36
	v_add_f32_e32 v37, 1.0, v44
	v_rcp_f32_e32 v36, v36
	v_rcp_f32_e32 v37, v37
	v_cvt_pk_bf16_f32 v32, v32, v33
	v_mul_f32_e32 v33, v46, v36
	v_mul_f32_e32 v36, v47, v37
	v_mul_f32_e32 v37, 0xbfb8aa3b, v40
	v_mul_f32_e32 v33, v38, v33
	v_exp_f32_e32 v37, v37
	v_mul_f32_e32 v38, 0xbfb8aa3b, v41
	v_exp_f32_e32 v38, v38
	v_mul_f32_e32 v36, v39, v36
	v_cvt_pk_bf16_f32 v33, v33, v36
	v_add_f32_e32 v36, 1.0, v37
	v_rcp_f32_e32 v36, v36
	v_add_f32_e32 v37, 1.0, v38
	v_mul_f32_e32 v38, 0xbfb8aa3b, v42
	v_rcp_f32_e32 v37, v37
	v_exp_f32_e32 v38, v38
	v_mul_f32_e32 v36, v40, v36
	v_mul_f32_e32 v34, v34, v36
	v_mul_f32_e32 v36, v41, v37
	v_add_f32_e32 v37, 1.0, v38
	v_rcp_f32_e32 v37, v37
	v_mul_f32_e32 v38, 0xbfb8aa3b, v43
	v_exp_f32_e32 v38, v38
	v_mul_f32_e32 v35, v35, v36
	v_cvt_pk_bf16_f32 v34, v34, v35
	v_mul_f32_e32 v35, v42, v37
	v_fmamk_f32 v37, v157, 0x3a800000, v154
	v_rsq_f32_e32 v37, v37
	v_add_f32_e32 v36, 1.0, v38
	v_rcp_f32_e32 v36, v36
	v_mul_f32_e32 v35, v52, v35
	v_mul_f32_e32 v36, v43, v36
	v_mul_f32_e32 v36, v53, v36
	v_cvt_pk_bf16_f32 v35, v35, v36
	flat_store_dwordx4 v[50:51], v[32:35]
	s_nop 1
	v_add_u32_e32 v33, 0xa0, v144
	s_nop 0
	s_nop 1
	s_nop 0
	v_mov_b32_e32 v32, v37
	v_pk_mul_f32 v[28:29], v[32:33], v[28:29] op_sel_hi:[0,1]
	v_mad_i64_i32 v[34:35], s[8:9], v33, s59, v[146:147]
	v_pk_mul_f32 v[30:31], v[32:33], v[30:31] op_sel_hi:[0,1]
	v_pk_mul_f32 v[26:27], v[32:33], v[26:27] op_sel_hi:[0,1]
	v_pk_mul_f32 v[24:25], v[32:33], v[24:25] op_sel_hi:[0,1]
	v_pk_mul_f32 v[22:23], v[32:33], v[22:23] op_sel_hi:[0,1]
	v_pk_mul_f32 v[20:21], v[32:33], v[20:21] op_sel_hi:[0,1]
	v_mul_f32_e32 v33, 0xbfb8aa3b, v28
	v_exp_f32_e32 v33, v33
	v_mul_f32_e32 v36, 0xbfb8aa3b, v29
	v_exp_f32_e32 v38, v36
	v_lshl_add_u64 v[34:35], v[34:35], 0, v[148:149]
	v_pk_mul_f32 v[36:37], v[32:33], v[18:19] op_sel_hi:[0,1]
	v_add_f32_e32 v18, 1.0, v33
	v_rcp_f32_e32 v33, v18
	v_add_f32_e32 v18, 1.0, v38
	v_rcp_f32_e32 v38, v18
	v_pk_mul_f32 v[18:19], v[32:33], v[16:17] op_sel_hi:[0,1]
	v_mul_f32_e32 v16, v28, v33
	v_mul_f32_e32 v16, v20, v16
	v_mul_f32_e32 v20, 0xbfb8aa3b, v30
	v_mul_f32_e32 v28, 0xbfb8aa3b, v31
	v_exp_f32_e32 v20, v20
	v_exp_f32_e32 v28, v28
	v_mul_f32_e32 v17, v29, v38
	v_mul_f32_e32 v17, v21, v17
	v_add_f32_e32 v20, 1.0, v20
	v_add_f32_e32 v21, 1.0, v28
	v_rcp_f32_e32 v20, v20
	v_rcp_f32_e32 v21, v21
	v_cvt_pk_bf16_f32 v16, v16, v17
	v_mul_f32_e32 v17, v30, v20
	v_mul_f32_e32 v20, v31, v21
	v_mul_f32_e32 v21, 0xbfb8aa3b, v24
	v_mul_f32_e32 v17, v22, v17
	v_exp_f32_e32 v21, v21
	v_mul_f32_e32 v22, 0xbfb8aa3b, v25
	v_exp_f32_e32 v22, v22
	v_mul_f32_e32 v20, v23, v20
	v_cvt_pk_bf16_f32 v17, v17, v20
	v_add_f32_e32 v20, 1.0, v21
	v_rcp_f32_e32 v20, v20
	v_add_f32_e32 v21, 1.0, v22
	v_mul_f32_e32 v22, 0xbfb8aa3b, v26
	v_rcp_f32_e32 v21, v21
	v_exp_f32_e32 v22, v22
	v_mul_f32_e32 v20, v24, v20
	v_mul_f32_e32 v18, v18, v20
	v_mul_f32_e32 v20, v25, v21
	v_add_f32_e32 v21, 1.0, v22
	v_rcp_f32_e32 v21, v21
	v_mul_f32_e32 v22, 0xbfb8aa3b, v27
	v_exp_f32_e32 v22, v22
	v_mul_f32_e32 v19, v19, v20
	v_cvt_pk_bf16_f32 v18, v18, v19
	v_mul_f32_e32 v19, v26, v21
	v_fmamk_f32 v21, v156, 0x3a800000, v154
	v_rsq_f32_e32 v21, v21
	v_add_f32_e32 v20, 1.0, v22
	v_rcp_f32_e32 v20, v20
	v_mul_f32_e32 v19, v36, v19
	v_mul_f32_e32 v20, v27, v20
	v_mul_f32_e32 v20, v37, v20
	v_cvt_pk_bf16_f32 v19, v19, v20
	flat_store_dwordx4 v[34:35], v[16:19]
	s_nop 1
	v_add_u32_e32 v17, 0xb0, v144
	s_nop 0
	s_nop 1
	s_nop 0
	v_mov_b32_e32 v16, v21
	v_pk_mul_f32 v[12:13], v[16:17], v[12:13] op_sel_hi:[0,1]
	v_mad_i64_i32 v[18:19], s[8:9], v17, s59, v[146:147]
	v_pk_mul_f32 v[14:15], v[16:17], v[14:15] op_sel_hi:[0,1]
	v_pk_mul_f32 v[10:11], v[16:17], v[10:11] op_sel_hi:[0,1]
	v_pk_mul_f32 v[8:9], v[16:17], v[8:9] op_sel_hi:[0,1]
	v_pk_mul_f32 v[6:7], v[16:17], v[6:7] op_sel_hi:[0,1]
	v_pk_mul_f32 v[4:5], v[16:17], v[4:5] op_sel_hi:[0,1]
	v_mul_f32_e32 v17, 0xbfb8aa3b, v12
	v_exp_f32_e32 v17, v17
	v_mul_f32_e32 v20, 0xbfb8aa3b, v13
	v_exp_f32_e32 v22, v20
	v_lshl_add_u64 v[18:19], v[18:19], 0, v[148:149]
	v_pk_mul_f32 v[20:21], v[16:17], v[2:3] op_sel_hi:[0,1]
	v_add_f32_e32 v2, 1.0, v17
	v_rcp_f32_e32 v17, v2
	v_add_f32_e32 v2, 1.0, v22
	v_rcp_f32_e32 v22, v2
	s_andn2_b64 vcc, exec, s[6:7]
	v_pk_mul_f32 v[2:3], v[16:17], v[0:1] op_sel_hi:[0,1]
	v_mul_f32_e32 v0, v12, v17
	v_mul_f32_e32 v0, v4, v0
	v_mul_f32_e32 v4, 0xbfb8aa3b, v14
	v_mul_f32_e32 v12, 0xbfb8aa3b, v15
	v_exp_f32_e32 v4, v4
	v_exp_f32_e32 v12, v12
	v_mul_f32_e32 v1, v13, v22
	v_mul_f32_e32 v1, v5, v1
	v_add_f32_e32 v4, 1.0, v4
	v_add_f32_e32 v5, 1.0, v12
	v_rcp_f32_e32 v4, v4
	v_rcp_f32_e32 v5, v5
	v_cvt_pk_bf16_f32 v0, v0, v1
	s_mov_b64 s[6:7], -1
	v_mul_f32_e32 v1, v14, v4
	v_mul_f32_e32 v4, v15, v5
	v_mul_f32_e32 v5, 0xbfb8aa3b, v8
	v_mul_f32_e32 v1, v6, v1
	v_exp_f32_e32 v5, v5
	v_mul_f32_e32 v6, 0xbfb8aa3b, v9
	v_exp_f32_e32 v6, v6
	v_mul_f32_e32 v4, v7, v4
	v_add_f32_e32 v5, 1.0, v5
	v_rcp_f32_e32 v5, v5
	v_add_f32_e32 v6, 1.0, v6
	v_rcp_f32_e32 v6, v6
	v_cvt_pk_bf16_f32 v1, v1, v4
	v_mul_f32_e32 v4, v8, v5
	v_mul_f32_e32 v5, 0xbfb8aa3b, v10
	v_mul_f32_e32 v2, v2, v4
	v_mul_f32_e32 v4, v9, v6
	v_exp_f32_e32 v5, v5
	v_mul_f32_e32 v6, 0xbfb8aa3b, v11
	v_exp_f32_e32 v6, v6
	v_mul_f32_e32 v3, v3, v4
	v_add_f32_e32 v4, 1.0, v5
	v_rcp_f32_e32 v4, v4
	v_add_f32_e32 v5, 1.0, v6
	v_rcp_f32_e32 v5, v5
	v_cvt_pk_bf16_f32 v2, v2, v3
	v_mul_f32_e32 v3, v10, v4
	v_mul_f32_e32 v3, v20, v3
	v_mul_f32_e32 v4, v11, v5
	v_mul_f32_e32 v4, v21, v4
	v_cvt_pk_bf16_f32 v3, v3, v4
	flat_store_dwordx4 v[18:19], v[0:3]
	s_cbranch_vccnz .LBB0_375
	s_andn2_b64 vcc, exec, s[10:11]
	s_cbranch_vccnz .LBB0_374
	s_barrier
	s_branch .LBB0_374

.LBB0_611:
	s_lshl_b32 s33, s84, 8
	s_waitcnt vmcnt(8)
	v_fmamk_f32 v192, v188, 0x3a800000, v177
	v_fmamk_f32 v190, v187, 0x3a800000, v177
	s_cmp_gt_i32 s84, 11
	s_mov_b64 s[10:11], -1
	v_cmp_gt_f32_e32 vcc, s73, v192
	v_mul_f32_e32 v193, 0x4f800000, v192
	v_or_b32_e32 v166, 16, v162
	v_cmp_gt_f32_e64 s[8:9], s73, v190
	v_mul_f32_e32 v191, 0x4f800000, v190
	v_or_b32_e32 v164, 32, v162
	v_fmamk_f32 v189, v186, 0x3a800000, v177
	s_cbranch_scc1 .LBB0_614
	s_andn2_b64 vcc, exec, s[10:11]
	s_cbranch_vccz .LBB0_615

.LBB0_2200:
	s_waitcnt vmcnt(8)
	v_fmamk_f32 v141, v159, 0x3a800000, v150
	v_mul_f32_e32 v142, 0x4f800000, v141
	v_cmp_gt_f32_e32 vcc, s49, v141
	s_nop 1
	v_cndmask_b32_e32 v141, v141, v142, vcc
	v_sqrt_f32_e32 v142, v141
	s_nop 0
	v_add_u32_e32 v143, -1, v142
	v_fma_f32 v145, -v143, v142, v141
	v_add_u32_e32 v144, 1, v142
	v_cmp_ge_f32_e64 s[8:9], 0, v145
	s_nop 1
	v_cndmask_b32_e64 v143, v142, v143, s[8:9]
	v_fma_f32 v142, -v144, v142, v141
	v_cmp_lt_f32_e64 s[8:9], 0, v142
	s_nop 1
	v_cndmask_b32_e64 v142, v143, v144, s[8:9]
	v_mul_f32_e32 v143, 0x37800000, v142
	v_cndmask_b32_e32 v142, v142, v143, vcc
	v_cmp_class_f32_e32 vcc, v141, v151
	v_lshl_or_b32 v144, s59, 8, v148
	v_ashrrev_i32_e32 v145, 31, v144
	v_cndmask_b32_e32 v141, v142, v141, vcc
	v_div_scale_f32 v142, s[8:9], v141, v141, 1.0
	v_rcp_f32_e32 v143, v142
	v_lshlrev_b64 v[144:145], 2, v[144:145]
	v_fma_f32 v160, -v142, v143, 1.0
	v_fmac_f32_e32 v143, v160, v143
	v_div_scale_f32 v160, vcc, 1.0, v141, 1.0
	v_mul_f32_e32 v161, v160, v143
	v_fma_f32 v162, -v142, v161, v160
	v_fmac_f32_e32 v161, v162, v143
	v_fma_f32 v142, -v142, v161, v160
	v_div_fmas_f32 v142, v142, v143, v161
	v_div_fixup_f32 v160, v142, v141, 1.0
	v_mov_b64_e32 v[142:143], s[12:13]
	v_mad_i64_i32 v[162:163], s[8:9], v140, s57, v[142:143]
	v_lshl_add_u64 v[162:163], v[162:163], 0, v[144:145]
	v_pk_mul_f32 v[122:123], v[122:123], v[160:161] op_sel_hi:[1,0]
	v_pk_mul_f32 v[120:121], v[120:121], v[160:161] op_sel_hi:[1,0]
	flat_store_dwordx4 v[162:163], v[120:123] offset:64
	v_pk_mul_f32 v[118:119], v[118:119], v[160:161] op_sel_hi:[1,0]
	v_pk_mul_f32 v[116:117], v[116:117], v[160:161] op_sel_hi:[1,0]
	v_fmamk_f32 v120, v158, 0x3a800000, v150
	v_mul_f32_e32 v121, 0x4f800000, v120
	v_cmp_gt_f32_e32 vcc, s49, v120
	flat_store_dwordx4 v[162:163], v[116:119] offset:512
	v_pk_mul_f32 v[110:111], v[110:111], v[160:161] op_sel_hi:[1,0]
	v_cndmask_b32_e32 v120, v120, v121, vcc
	v_sqrt_f32_e32 v121, v120
	v_pk_mul_f32 v[108:109], v[108:109], v[160:161] op_sel_hi:[1,0]
	flat_store_dwordx4 v[162:163], v[108:111] offset:576
	v_pk_mul_f32 v[126:127], v[126:127], v[160:161] op_sel_hi:[1,0]
	v_add_u32_e32 v116, -1, v121
	v_fma_f32 v117, -v116, v121, v120
	v_cmp_ge_f32_e64 s[8:9], 0, v117
	v_add_u32_e32 v117, 1, v121
	v_fma_f32 v118, -v117, v121, v120
	v_cndmask_b32_e64 v116, v121, v116, s[8:9]
	v_cmp_lt_f32_e64 s[8:9], 0, v118
	v_or_b32_e32 v108, 16, v140
	v_pk_mul_f32 v[124:125], v[124:125], v[160:161] op_sel_hi:[1,0]
	v_cndmask_b32_e64 v116, v116, v117, s[8:9]
	v_mul_f32_e32 v117, 0x37800000, v116
	v_cndmask_b32_e32 v116, v116, v117, vcc
	v_cmp_class_f32_e32 vcc, v120, v151
	flat_store_dwordx4 v[162:163], v[124:127]
	s_nop 0
	v_cndmask_b32_e32 v116, v116, v120, vcc
	v_div_scale_f32 v117, s[8:9], v116, v116, 1.0
	v_rcp_f32_e32 v118, v117
	s_nop 0
	v_fma_f32 v109, -v117, v118, 1.0
	v_fmac_f32_e32 v118, v109, v118
	v_div_scale_f32 v109, vcc, 1.0, v116, 1.0
	v_mul_f32_e32 v110, v109, v118
	v_fma_f32 v111, -v117, v110, v109
	v_fmac_f32_e32 v110, v111, v118
	v_fma_f32 v109, -v117, v110, v109
	v_div_fmas_f32 v109, v109, v118, v110
	v_div_fixup_f32 v116, v109, v116, 1.0
	v_mad_i64_i32 v[108:109], s[8:9], v108, s57, v[142:143]
	v_lshl_add_u64 v[118:119], v[108:109], 0, v[144:145]
	v_pk_mul_f32 v[106:107], v[116:117], v[106:107] op_sel_hi:[0,1]
	v_pk_mul_f32 v[104:105], v[116:117], v[104:105] op_sel_hi:[0,1]
	flat_store_dwordx4 v[118:119], v[104:107] offset:64
	v_pk_mul_f32 v[102:103], v[116:117], v[102:103] op_sel_hi:[0,1]
	v_pk_mul_f32 v[100:101], v[116:117], v[100:101] op_sel_hi:[0,1]
	v_fmamk_f32 v104, v157, 0x3a800000, v150
	v_mul_f32_e32 v105, 0x4f800000, v104
	v_cmp_gt_f32_e32 vcc, s49, v104
	flat_store_dwordx4 v[118:119], v[100:103] offset:512
	v_pk_mul_f32 v[94:95], v[116:117], v[94:95] op_sel_hi:[0,1]
	v_cndmask_b32_e32 v104, v104, v105, vcc
	v_sqrt_f32_e32 v105, v104
	v_pk_mul_f32 v[92:93], v[116:117], v[92:93] op_sel_hi:[0,1]
	flat_store_dwordx4 v[118:119], v[92:95] offset:576
	v_pk_mul_f32 v[110:111], v[116:117], v[114:115] op_sel_hi:[0,1]
	v_add_u32_e32 v100, -1, v105
	v_fma_f32 v101, -v100, v105, v104
	v_cmp_ge_f32_e64 s[8:9], 0, v101
	v_add_u32_e32 v101, 1, v105
	v_fma_f32 v102, -v101, v105, v104
	v_cndmask_b32_e64 v100, v105, v100, s[8:9]
	v_cmp_lt_f32_e64 s[8:9], 0, v102
	v_or_b32_e32 v92, 32, v140
	v_pk_mul_f32 v[108:109], v[116:117], v[112:113] op_sel_hi:[0,1]
	v_cndmask_b32_e64 v100, v100, v101, s[8:9]
	v_mul_f32_e32 v101, 0x37800000, v100
	v_cndmask_b32_e32 v100, v100, v101, vcc
	v_cmp_class_f32_e32 vcc, v104, v151
	flat_store_dwordx4 v[118:119], v[108:111]
	s_nop 0
	v_cndmask_b32_e32 v100, v100, v104, vcc
	v_div_scale_f32 v101, s[8:9], v100, v100, 1.0
	v_rcp_f32_e32 v102, v101
	s_nop 0
	v_fma_f32 v93, -v101, v102, 1.0
	v_fmac_f32_e32 v102, v93, v102
	v_div_scale_f32 v93, vcc, 1.0, v100, 1.0
	v_mul_f32_e32 v94, v93, v102
	v_fma_f32 v95, -v101, v94, v93
	v_fmac_f32_e32 v94, v95, v102
	v_fma_f32 v93, -v101, v94, v93
	v_div_fmas_f32 v93, v93, v102, v94
	v_div_fixup_f32 v100, v93, v100, 1.0
	v_mad_i64_i32 v[92:93], s[8:9], v92, s57, v[142:143]
	v_lshl_add_u64 v[102:103], v[92:93], 0, v[144:145]
	v_pk_mul_f32 v[90:91], v[100:101], v[90:91] op_sel_hi:[0,1]
	v_pk_mul_f32 v[88:89], v[100:101], v[88:89] op_sel_hi:[0,1]
	flat_store_dwordx4 v[102:103], v[88:91] offset:64
	v_pk_mul_f32 v[86:87], v[100:101], v[86:87] op_sel_hi:[0,1]
	v_pk_mul_f32 v[84:85], v[100:101], v[84:85] op_sel_hi:[0,1]
	v_fmamk_f32 v88, v156, 0x3a800000, v150
	v_mul_f32_e32 v89, 0x4f800000, v88
	v_cmp_gt_f32_e32 vcc, s49, v88
	flat_store_dwordx4 v[102:103], v[84:87] offset:512
	v_pk_mul_f32 v[78:79], v[100:101], v[78:79] op_sel_hi:[0,1]
	v_cndmask_b32_e32 v88, v88, v89, vcc
	v_sqrt_f32_e32 v89, v88
	v_pk_mul_f32 v[76:77], v[100:101], v[76:77] op_sel_hi:[0,1]
	flat_store_dwordx4 v[102:103], v[76:79] offset:576
	v_pk_mul_f32 v[94:95], v[100:101], v[98:99] op_sel_hi:[0,1]
	v_add_u32_e32 v84, -1, v89
	v_fma_f32 v85, -v84, v89, v88
	v_cmp_ge_f32_e64 s[8:9], 0, v85
	v_add_u32_e32 v85, 1, v89
	v_fma_f32 v86, -v85, v89, v88
	v_cndmask_b32_e64 v84, v89, v84, s[8:9]
	v_cmp_lt_f32_e64 s[8:9], 0, v86
	v_or_b32_e32 v76, 48, v140
	v_pk_mul_f32 v[92:93], v[100:101], v[96:97] op_sel_hi:[0,1]
	v_cndmask_b32_e64 v84, v84, v85, s[8:9]
	v_mul_f32_e32 v85, 0x37800000, v84
	v_cndmask_b32_e32 v84, v84, v85, vcc
	v_cmp_class_f32_e32 vcc, v88, v151
	flat_store_dwordx4 v[102:103], v[92:95]
	s_nop 0
	v_cndmask_b32_e32 v84, v84, v88, vcc
	v_div_scale_f32 v85, s[8:9], v84, v84, 1.0
	v_rcp_f32_e32 v86, v85
	s_nop 0
	v_fma_f32 v77, -v85, v86, 1.0
	v_fmac_f32_e32 v86, v77, v86
	v_div_scale_f32 v77, vcc, 1.0, v84, 1.0
	v_mul_f32_e32 v78, v77, v86
	v_fma_f32 v79, -v85, v78, v77
	v_fmac_f32_e32 v78, v79, v86
	v_fma_f32 v77, -v85, v78, v77
	v_div_fmas_f32 v77, v77, v86, v78
	v_div_fixup_f32 v84, v77, v84, 1.0
	v_mad_i64_i32 v[76:77], s[8:9], v76, s57, v[142:143]
	v_lshl_add_u64 v[86:87], v[76:77], 0, v[144:145]
	v_pk_mul_f32 v[74:75], v[84:85], v[74:75] op_sel_hi:[0,1]
	v_pk_mul_f32 v[72:73], v[84:85], v[72:73] op_sel_hi:[0,1]
	flat_store_dwordx4 v[86:87], v[72:75] offset:64
	v_pk_mul_f32 v[70:71], v[84:85], v[70:71] op_sel_hi:[0,1]
	v_pk_mul_f32 v[68:69], v[84:85], v[68:69] op_sel_hi:[0,1]
	v_fmamk_f32 v72, v155, 0x3a800000, v150
	v_mul_f32_e32 v73, 0x4f800000, v72
	v_cmp_gt_f32_e32 vcc, s49, v72
	flat_store_dwordx4 v[86:87], v[68:71] offset:512
	v_pk_mul_f32 v[66:67], v[84:85], v[66:67] op_sel_hi:[0,1]
	v_cndmask_b32_e32 v72, v72, v73, vcc
	v_sqrt_f32_e32 v73, v72
	v_pk_mul_f32 v[64:65], v[84:85], v[64:65] op_sel_hi:[0,1]
	flat_store_dwordx4 v[86:87], v[64:67] offset:576
	v_pk_mul_f32 v[78:79], v[84:85], v[82:83] op_sel_hi:[0,1]
	v_add_u32_e32 v68, -1, v73
	v_fma_f32 v69, -v68, v73, v72
	v_cmp_ge_f32_e64 s[8:9], 0, v69
	v_add_u32_e32 v69, 1, v73
	v_fma_f32 v70, -v69, v73, v72
	v_cndmask_b32_e64 v68, v73, v68, s[8:9]
	v_cmp_lt_f32_e64 s[8:9], 0, v70
	v_add_u32_e32 v65, 0x80, v140
	v_pk_mul_f32 v[76:77], v[84:85], v[80:81] op_sel_hi:[0,1]
	v_cndmask_b32_e64 v68, v68, v69, s[8:9]
	v_mul_f32_e32 v69, 0x37800000, v68
	v_cndmask_b32_e32 v68, v68, v69, vcc
	v_cmp_class_f32_e32 vcc, v72, v151
	flat_store_dwordx4 v[86:87], v[76:79]
	s_nop 0
	v_cndmask_b32_e32 v68, v68, v72, vcc
	v_div_scale_f32 v69, s[8:9], v68, v68, 1.0
	v_rcp_f32_e32 v70, v69
	s_nop 0
	v_fma_f32 v64, -v69, v70, 1.0
	v_fmac_f32_e32 v70, v64, v70
	v_div_scale_f32 v64, vcc, 1.0, v68, 1.0
	v_mul_f32_e32 v66, v64, v70
	v_fma_f32 v67, -v69, v66, v64
	v_fmac_f32_e32 v66, v67, v70
	v_fma_f32 v64, -v69, v66, v64
	v_div_fmas_f32 v64, v64, v70, v66
	v_div_fixup_f32 v64, v64, v68, 1.0
	v_mad_i64_i32 v[66:67], s[8:9], v65, s57, v[142:143]
	v_lshl_add_u64 v[66:67], v[66:67], 0, v[144:145]
	v_pk_mul_f32 v[58:59], v[64:65], v[58:59] op_sel_hi:[0,1]
	v_pk_mul_f32 v[56:57], v[64:65], v[56:57] op_sel_hi:[0,1]
	flat_store_dwordx4 v[66:67], v[56:59] offset:64
	v_pk_mul_f32 v[54:55], v[64:65], v[54:55] op_sel_hi:[0,1]
	v_pk_mul_f32 v[52:53], v[64:65], v[52:53] op_sel_hi:[0,1]
	v_fmamk_f32 v56, v154, 0x3a800000, v150
	v_mul_f32_e32 v57, 0x4f800000, v56
	v_cmp_gt_f32_e32 vcc, s49, v56
	flat_store_dwordx4 v[66:67], v[52:55] offset:512
	v_pk_mul_f32 v[46:47], v[64:65], v[46:47] op_sel_hi:[0,1]
	v_cndmask_b32_e32 v56, v56, v57, vcc
	v_sqrt_f32_e32 v57, v56
	v_pk_mul_f32 v[44:45], v[64:65], v[44:45] op_sel_hi:[0,1]
	flat_store_dwordx4 v[66:67], v[44:47] offset:576
	v_pk_mul_f32 v[62:63], v[64:65], v[62:63] op_sel_hi:[0,1]
	v_add_u32_e32 v52, -1, v57
	v_fma_f32 v53, -v52, v57, v56
	v_cmp_ge_f32_e64 s[8:9], 0, v53
	v_add_u32_e32 v53, 1, v57
	v_fma_f32 v54, -v53, v57, v56
	v_cndmask_b32_e64 v52, v57, v52, s[8:9]
	v_cmp_lt_f32_e64 s[8:9], 0, v54
	v_add_u32_e32 v44, 0x90, v140
	v_pk_mul_f32 v[60:61], v[64:65], v[60:61] op_sel_hi:[0,1]
	v_cndmask_b32_e64 v52, v52, v53, s[8:9]
	v_mul_f32_e32 v53, 0x37800000, v52
	v_cndmask_b32_e32 v52, v52, v53, vcc
	v_cmp_class_f32_e32 vcc, v56, v151
	flat_store_dwordx4 v[66:67], v[60:63]
	s_nop 0
	v_cndmask_b32_e32 v52, v52, v56, vcc
	v_div_scale_f32 v53, s[8:9], v52, v52, 1.0
	v_rcp_f32_e32 v54, v53
	s_nop 0
	v_fma_f32 v45, -v53, v54, 1.0
	v_fmac_f32_e32 v54, v45, v54
	v_div_scale_f32 v45, vcc, 1.0, v52, 1.0
	v_mul_f32_e32 v46, v45, v54
	v_fma_f32 v47, -v53, v46, v45
	v_fmac_f32_e32 v46, v47, v54
	v_fma_f32 v45, -v53, v46, v45
	v_div_fmas_f32 v45, v45, v54, v46
	v_div_fixup_f32 v52, v45, v52, 1.0
	v_mad_i64_i32 v[44:45], s[8:9], v44, s57, v[142:143]
	v_lshl_add_u64 v[54:55], v[44:45], 0, v[144:145]
	v_pk_mul_f32 v[42:43], v[52:53], v[42:43] op_sel_hi:[0,1]
	v_pk_mul_f32 v[40:41], v[52:53], v[40:41] op_sel_hi:[0,1]
	flat_store_dwordx4 v[54:55], v[40:43] offset:64
	v_pk_mul_f32 v[38:39], v[52:53], v[38:39] op_sel_hi:[0,1]
	v_pk_mul_f32 v[36:37], v[52:53], v[36:37] op_sel_hi:[0,1]
	v_fmamk_f32 v40, v153, 0x3a800000, v150
	v_mul_f32_e32 v41, 0x4f800000, v40
	v_cmp_gt_f32_e32 vcc, s49, v40
	flat_store_dwordx4 v[54:55], v[36:39] offset:512
	v_pk_mul_f32 v[30:31], v[52:53], v[30:31] op_sel_hi:[0,1]
	v_cndmask_b32_e32 v40, v40, v41, vcc
	v_sqrt_f32_e32 v41, v40
	v_pk_mul_f32 v[28:29], v[52:53], v[28:29] op_sel_hi:[0,1]
	flat_store_dwordx4 v[54:55], v[28:31] offset:576
	v_pk_mul_f32 v[46:47], v[52:53], v[50:51] op_sel_hi:[0,1]
	v_add_u32_e32 v36, -1, v41
	v_fma_f32 v37, -v36, v41, v40
	v_cmp_ge_f32_e64 s[8:9], 0, v37
	v_add_u32_e32 v37, 1, v41
	v_fma_f32 v38, -v37, v41, v40
	v_cndmask_b32_e64 v36, v41, v36, s[8:9]
	v_cmp_lt_f32_e64 s[8:9], 0, v38
	v_add_u32_e32 v28, 0xa0, v140
	v_pk_mul_f32 v[44:45], v[52:53], v[48:49] op_sel_hi:[0,1]
	v_cndmask_b32_e64 v36, v36, v37, s[8:9]
	v_mul_f32_e32 v37, 0x37800000, v36
	v_cndmask_b32_e32 v36, v36, v37, vcc
	v_cmp_class_f32_e32 vcc, v40, v151
	flat_store_dwordx4 v[54:55], v[44:47]
	s_nop 0
	v_cndmask_b32_e32 v36, v36, v40, vcc
	v_div_scale_f32 v37, s[8:9], v36, v36, 1.0
	v_rcp_f32_e32 v38, v37
	s_nop 0
	v_fma_f32 v29, -v37, v38, 1.0
	v_fmac_f32_e32 v38, v29, v38
	v_div_scale_f32 v29, vcc, 1.0, v36, 1.0
	v_mul_f32_e32 v30, v29, v38
	v_fma_f32 v31, -v37, v30, v29
	v_fmac_f32_e32 v30, v31, v38
	v_fma_f32 v29, -v37, v30, v29
	v_div_fmas_f32 v29, v29, v38, v30
	v_div_fixup_f32 v36, v29, v36, 1.0
	v_mad_i64_i32 v[28:29], s[8:9], v28, s57, v[142:143]
	v_lshl_add_u64 v[38:39], v[28:29], 0, v[144:145]
	v_pk_mul_f32 v[26:27], v[36:37], v[26:27] op_sel_hi:[0,1]
	v_pk_mul_f32 v[24:25], v[36:37], v[24:25] op_sel_hi:[0,1]
	flat_store_dwordx4 v[38:39], v[24:27] offset:64
	v_pk_mul_f32 v[22:23], v[36:37], v[22:23] op_sel_hi:[0,1]
	v_pk_mul_f32 v[20:21], v[36:37], v[20:21] op_sel_hi:[0,1]
	v_fmamk_f32 v24, v152, 0x3a800000, v150
	v_mul_f32_e32 v25, 0x4f800000, v24
	v_cmp_gt_f32_e32 vcc, s49, v24
	flat_store_dwordx4 v[38:39], v[20:23] offset:512
	v_pk_mul_f32 v[14:15], v[36:37], v[14:15] op_sel_hi:[0,1]
	v_cndmask_b32_e32 v24, v24, v25, vcc
	v_sqrt_f32_e32 v25, v24
	v_pk_mul_f32 v[12:13], v[36:37], v[12:13] op_sel_hi:[0,1]
	flat_store_dwordx4 v[38:39], v[12:15] offset:576
	v_pk_mul_f32 v[30:31], v[36:37], v[34:35] op_sel_hi:[0,1]
	v_add_u32_e32 v20, -1, v25
	v_fma_f32 v21, -v20, v25, v24
	v_cmp_ge_f32_e64 s[8:9], 0, v21
	v_add_u32_e32 v21, 1, v25
	v_fma_f32 v22, -v21, v25, v24
	v_cndmask_b32_e64 v20, v25, v20, s[8:9]
	v_cmp_lt_f32_e64 s[8:9], 0, v22
	v_add_u32_e32 v12, 0xb0, v140
	v_pk_mul_f32 v[28:29], v[36:37], v[32:33] op_sel_hi:[0,1]
	v_cndmask_b32_e64 v20, v20, v21, s[8:9]
	v_mul_f32_e32 v21, 0x37800000, v20
	v_cndmask_b32_e32 v20, v20, v21, vcc
	v_cmp_class_f32_e32 vcc, v24, v151
	flat_store_dwordx4 v[38:39], v[28:31]
	s_nop 0
	v_cndmask_b32_e32 v20, v20, v24, vcc
	v_div_scale_f32 v21, s[8:9], v20, v20, 1.0
	v_rcp_f32_e32 v22, v21
	s_nop 0
	v_fma_f32 v13, -v21, v22, 1.0
	v_fmac_f32_e32 v22, v13, v22
	v_div_scale_f32 v13, vcc, 1.0, v20, 1.0
	v_mul_f32_e32 v14, v13, v22
	v_fma_f32 v15, -v21, v14, v13
	v_fmac_f32_e32 v14, v15, v22
	v_fma_f32 v13, -v21, v14, v13
	v_div_fmas_f32 v13, v13, v22, v14
	v_div_fixup_f32 v20, v13, v20, 1.0
	v_mad_i64_i32 v[12:13], s[8:9], v12, s57, v[142:143]
	v_lshl_add_u64 v[22:23], v[12:13], 0, v[144:145]
	v_pk_mul_f32 v[14:15], v[20:21], v[18:19] op_sel_hi:[0,1]
	v_pk_mul_f32 v[12:13], v[20:21], v[16:17] op_sel_hi:[0,1]
	v_pk_mul_f32 v[10:11], v[20:21], v[10:11] op_sel_hi:[0,1]
	v_pk_mul_f32 v[8:9], v[20:21], v[8:9] op_sel_hi:[0,1]
	v_pk_mul_f32 v[6:7], v[20:21], v[6:7] op_sel_hi:[0,1]
	v_pk_mul_f32 v[4:5], v[20:21], v[4:5] op_sel_hi:[0,1]
	v_pk_mul_f32 v[2:3], v[20:21], v[2:3] op_sel_hi:[0,1]
	v_pk_mul_f32 v[0:1], v[20:21], v[0:1] op_sel_hi:[0,1]
	s_andn2_b64 vcc, exec, s[6:7]
	s_mov_b64 s[6:7], -1
	flat_store_dwordx4 v[22:23], v[12:15]
	flat_store_dwordx4 v[22:23], v[8:11] offset:64
	flat_store_dwordx4 v[22:23], v[4:7] offset:512
	flat_store_dwordx4 v[22:23], v[0:3] offset:576
	s_cbranch_vccnz .LBB0_2191
	s_andn2_b64 vcc, exec, s[10:11]
	s_cbranch_vccnz .LBB0_2190
	s_barrier
	s_branch .LBB0_2190
